# in-proj GEMM epilogue: the 16 per-wave LDS transposes software-pipelined (two register sets, wait lgkmcnt(2) instead of draining after every transpose)
# baseline (speedup 1.0000x reference)
; #define PG8_LAS __attribute__((address_space(3)))
; __device__ __forceinline__ unsigned cvt_pk_bf16(float lo, float hi) { unsigned r; asm volatile("v_cvt_pk_bf16_f32 %0, %1, %2" : "=v"(r) : "v"(lo), "v"(hi)); return r; }
;     __device__ __forceinline__ void operator()(const f32x4 (&acc)[2][2][4][2], const Unit& u, int wr, int wc, int fr, int fq) const {
;         const int row0 = u.pm * BM + wr * 64 + fr; const int col0 = u.pn * BM + wc * 32 + 8 * fq;
; #pragma unroll
;         for (int ai = 0; ai < 2; ++ai)
; #pragma unroll
;             for (int m = 0; m < 4; ++m) {
; #pragma unroll
;                 for (int bj = 0; bj < 2; ++bj) { const f32x4 v0 = acc[ai][bj][m][0], v1 = acc[ai][bj][m][1];
;                     u32x4 w; w.x = cvt_pk_bf16(v0[0], v0[1]); w.y = cvt_pk_bf16(v0[2], v0[3]); w.z = cvt_pk_bf16(v1[0], v1[1]); w.w = cvt_pk_bf16(v1[2], v1[3]);
;                     PG8_LAS unsigned char* tl = epl + (wr * 4 + wc) * 2048 + ((ai * 4 + m) * 2 + bj) % 2 * 1024;
;                     const int ln = fq * 16 + fr;
;                     *(PG8_LAS u32x4*)(tl + fr * 64 + ((fq ^ (fr >> 2)) & 3) * 16) = w;
;                     const int r2 = ln >> 2, p2 = ln & 3;
;                     const u32x4 w2 = *(const PG8_LAS u32x4*)(tl + r2 * 64 + ((p2 ^ (r2 >> 2)) & 3) * 16);
;                     const int cc = u.pn * BM + bj * HALF + wc * 32;
;                     bf16_t* dst = O + ((size_t)(cc >> 6) * 16384 + (size_t)(u.pm * BM + wr * 64 + ai * HALF + m * 16 + r2)) * 64 + (cc & 63) + p2 * 8;
;                     *(u32x4*)dst = w2; } }
.LBB0_178:
	s_lshl_b32 s31, s64, 8
	s_or_b32 s31, s31, s60
	s_ashr_i32 s48, s31, 6
	s_ashr_i32 s49, s48, 31
	s_lshl_b32 s31, s65, 8
	v_cvt_pk_bf16_f32 v154, v128, v129
	v_cvt_pk_bf16_f32 v155, v130, v131
	v_cvt_pk_bf16_f32 v156, v124, v125
	v_cvt_pk_bf16_f32 v157, v126, v127
	ds_write_b128 v152, v[154:157]
	v_add_u32_e32 v144, s31, v147
	s_lshl_b64 s[46:47], s[48:49], 21
	ds_read_b128 v[154:157], v153
	v_ashrrev_i32_e32 v145, 31, v144
	s_add_u32 s46, s10, s46
	s_addc_u32 s47, s11, s47
	v_lshlrev_b64 v[158:159], 7, v[144:145]
	v_lshl_add_u64 v[160:161], s[46:47], 0, v[158:159]
	v_lshl_add_u64 v[160:161], v[160:161], 0, s[34:35]
	s_or_b32 s48, s48, 2
	v_lshl_add_u64 v[160:161], v[160:161], 0, v[188:189]
	s_ashr_i32 s49, s48, 31
	s_lshl_b64 s[48:49], s[48:49], 21
	s_add_u32 s48, s10, s48
	v_cvt_pk_bf16_f32 v162, v116, v117
	v_cvt_pk_bf16_f32 v163, v118, v119
	v_cvt_pk_bf16_f32 v164, v108, v109
	v_cvt_pk_bf16_f32 v165, v110, v111
	ds_write_b128 v152, v[162:165] offset:1024
	ds_read_b128 v[162:165], v153 offset:1024
	s_addc_u32 s49, s11, s49
	v_lshl_add_u64 v[158:159], s[48:49], 0, v[158:159]
	v_lshl_add_u64 v[158:159], v[158:159], 0, s[34:35]
	v_lshl_add_u64 v[158:159], v[158:159], 0, v[188:189]
	s_waitcnt lgkmcnt(2)
	global_store_dwordx4 v[160:161], v[154:157], off
	s_nop 1
	v_add_u32_e32 v168, s31, v148
	v_ashrrev_i32_e32 v169, 31, v168
	v_cvt_pk_bf16_f32 v154, v120, v121
	v_cvt_pk_bf16_f32 v155, v122, v123
	v_cvt_pk_bf16_f32 v156, v112, v113
	v_cvt_pk_bf16_f32 v157, v114, v115
	ds_write_b128 v152, v[154:157]
	ds_read_b128 v[154:157], v153
	v_lshlrev_b64 v[168:169], 7, v[168:169]
	v_lshl_add_u64 v[170:171], s[46:47], 0, v[168:169]
	v_lshl_add_u64 v[170:171], v[170:171], 0, s[34:35]
	v_lshl_add_u64 v[170:171], v[170:171], 0, v[188:189]
	s_waitcnt lgkmcnt(2)
	global_store_dwordx4 v[158:159], v[162:165], off
	s_nop 1
	v_lshl_add_u64 v[168:169], s[48:49], 0, v[168:169]
	v_lshl_add_u64 v[168:169], v[168:169], 0, s[34:35]
	v_cvt_pk_bf16_f32 v162, v100, v101
	v_cvt_pk_bf16_f32 v163, v102, v103
	v_cvt_pk_bf16_f32 v164, v92, v93
	v_cvt_pk_bf16_f32 v165, v94, v95
	ds_write_b128 v152, v[162:165] offset:1024
	ds_read_b128 v[162:165], v153 offset:1024
	v_lshl_add_u64 v[168:169], v[168:169], 0, v[188:189]
	v_readlane_b32 s75, v255, 25
	s_mov_b32 s89, 0x2aaaaaab
	s_cmp_lt_i32 s64, 5
	s_waitcnt lgkmcnt(2)
	global_store_dwordx4 v[170:171], v[154:157], off
	s_nop 1
	v_add_u32_e32 v158, s31, v149
	v_ashrrev_i32_e32 v159, 31, v158
	v_cvt_pk_bf16_f32 v154, v104, v105
	v_cvt_pk_bf16_f32 v155, v106, v107
	v_cvt_pk_bf16_f32 v156, v96, v97
	v_cvt_pk_bf16_f32 v157, v98, v99
	ds_write_b128 v152, v[154:157]
	ds_read_b128 v[154:157], v153
	v_lshlrev_b64 v[158:159], 7, v[158:159]
	v_lshl_add_u64 v[160:161], s[46:47], 0, v[158:159]
	v_lshl_add_u64 v[160:161], v[160:161], 0, s[34:35]
	v_lshl_add_u64 v[160:161], v[160:161], 0, v[188:189]
	s_waitcnt lgkmcnt(2)
	global_store_dwordx4 v[168:169], v[162:165], off
	s_nop 1
	v_lshl_add_u64 v[158:159], s[48:49], 0, v[158:159]
	v_lshl_add_u64 v[158:159], v[158:159], 0, s[34:35]
	v_cvt_pk_bf16_f32 v162, v84, v85
	v_cvt_pk_bf16_f32 v163, v86, v87
	v_cvt_pk_bf16_f32 v164, v76, v77
	v_cvt_pk_bf16_f32 v165, v78, v79
	ds_write_b128 v152, v[162:165] offset:1024
	ds_read_b128 v[162:165], v153 offset:1024
	v_lshl_add_u64 v[158:159], v[158:159], 0, v[188:189]
	s_waitcnt lgkmcnt(2)
	global_store_dwordx4 v[160:161], v[154:157], off
	s_nop 1
	v_cvt_pk_bf16_f32 v154, v88, v89
	v_cvt_pk_bf16_f32 v155, v90, v91
	v_cvt_pk_bf16_f32 v156, v80, v81
	v_cvt_pk_bf16_f32 v157, v82, v83
	ds_write_b128 v152, v[154:157]
	v_add_u32_e32 v168, s31, v150
	ds_read_b128 v[154:157], v153
	v_ashrrev_i32_e32 v169, 31, v168
	v_lshlrev_b64 v[168:169], 7, v[168:169]
	v_lshl_add_u64 v[170:171], s[46:47], 0, v[168:169]
	v_lshl_add_u64 v[170:171], v[170:171], 0, s[34:35]
	v_lshl_add_u64 v[170:171], v[170:171], 0, v[188:189]
	s_waitcnt lgkmcnt(2)
	global_store_dwordx4 v[158:159], v[162:165], off
	s_nop 1
	v_lshl_add_u64 v[168:169], s[48:49], 0, v[168:169]
	v_lshl_add_u64 v[168:169], v[168:169], 0, s[34:35]
	v_cvt_pk_bf16_f32 v162, v72, v73
	v_cvt_pk_bf16_f32 v163, v74, v75
	v_cvt_pk_bf16_f32 v164, v68, v69
	v_cvt_pk_bf16_f32 v165, v70, v71
	ds_write_b128 v152, v[162:165] offset:1024
	ds_read_b128 v[162:165], v153 offset:1024
	v_lshl_add_u64 v[168:169], v[168:169], 0, v[188:189]
	s_waitcnt lgkmcnt(2)
; #define PG8_LAS __attribute__((address_space(3)))
; __device__ __forceinline__ unsigned cvt_pk_bf16(float lo, float hi) { unsigned r; asm volatile("v_cvt_pk_bf16_f32 %0, %1, %2" : "=v"(r) : "v"(lo), "v"(hi)); return r; }
;     __device__ __forceinline__ void operator()(const f32x4 (&acc)[2][2][4][2], const Unit& u, int wr, int wc, int fr, int fq) const {
;     ...
;                 for (int bj = 0; bj < 2; ++bj) { const f32x4 v0 = acc[ai][bj][m][0], v1 = acc[ai][bj][m][1];
;                     u32x4 w; w.x = cvt_pk_bf16(v0[0], v0[1]); w.y = cvt_pk_bf16(v0[2], v0[3]); w.z = cvt_pk_bf16(v1[0], v1[1]); w.w = cvt_pk_bf16(v1[2], v1[3]);
;                     PG8_LAS unsigned char* tl = epl + (wr * 4 + wc) * 2048 + ((ai * 4 + m) * 2 + bj) % 2 * 1024;
;                     const int ln = fq * 16 + fr;
;                     *(PG8_LAS u32x4*)(tl + fr * 64 + ((fq ^ (fr >> 2)) & 3) * 16) = w;
;                     const int r2 = ln >> 2, p2 = ln & 3;
;                     const u32x4 w2 = *(const PG8_LAS u32x4*)(tl + r2 * 64 + ((p2 ^ (r2 >> 2)) & 3) * 16);
;                     const int cc = u.pn * BM + bj * HALF + wc * 32;
;                     bf16_t* dst = O + ((size_t)(cc >> 6) * 16384 + (size_t)(u.pm * BM + wr * 64 + ai * HALF + m * 16 + r2)) * 64 + (cc & 63) + p2 * 8;
;                     *(u32x4*)dst = w2; } }
;         if (u.pn == 1 || u.pn == 5 || u.pn == 13) {
	global_store_dwordx4 v[170:171], v[154:157], off
	s_nop 1
	v_cvt_pk_bf16_f32 v154, v64, v65
	v_cvt_pk_bf16_f32 v155, v66, v67
	v_cvt_pk_bf16_f32 v156, v60, v61
	v_cvt_pk_bf16_f32 v157, v62, v63
	ds_write_b128 v152, v[154:157]
	v_add_u32_e32 v158, 0x80, v144
	ds_read_b128 v[154:157], v153
	v_ashrrev_i32_e32 v159, 31, v158
	v_lshlrev_b64 v[158:159], 7, v[158:159]
	v_lshl_add_u64 v[160:161], s[46:47], 0, v[158:159]
	v_lshl_add_u64 v[160:161], v[160:161], 0, s[34:35]
	v_lshl_add_u64 v[160:161], v[160:161], 0, v[188:189]
	s_waitcnt lgkmcnt(2)
	global_store_dwordx4 v[168:169], v[162:165], off
	s_nop 1
	v_lshl_add_u64 v[158:159], s[48:49], 0, v[158:159]
	v_lshl_add_u64 v[158:159], v[158:159], 0, s[34:35]
	v_cvt_pk_bf16_f32 v162, v52, v53
	v_cvt_pk_bf16_f32 v163, v54, v55
	v_cvt_pk_bf16_f32 v164, v44, v45
	v_cvt_pk_bf16_f32 v165, v46, v47
	ds_write_b128 v152, v[162:165] offset:1024
	ds_read_b128 v[162:165], v153 offset:1024
	v_lshl_add_u64 v[158:159], v[158:159], 0, v[188:189]
	s_waitcnt lgkmcnt(2)
	global_store_dwordx4 v[160:161], v[154:157], off
	s_nop 1
	v_cvt_pk_bf16_f32 v154, v56, v57
	v_cvt_pk_bf16_f32 v155, v58, v59
	v_cvt_pk_bf16_f32 v156, v48, v49
	v_cvt_pk_bf16_f32 v157, v50, v51
	ds_write_b128 v152, v[154:157]
	v_add_u32_e32 v168, 0x90, v144
	ds_read_b128 v[154:157], v153
	v_ashrrev_i32_e32 v169, 31, v168
	v_lshlrev_b64 v[168:169], 7, v[168:169]
	v_lshl_add_u64 v[170:171], s[46:47], 0, v[168:169]
	v_lshl_add_u64 v[170:171], v[170:171], 0, s[34:35]
	v_lshl_add_u64 v[170:171], v[170:171], 0, v[188:189]
	s_waitcnt lgkmcnt(2)
	global_store_dwordx4 v[158:159], v[162:165], off
	s_nop 1
	v_lshl_add_u64 v[168:169], s[48:49], 0, v[168:169]
	v_lshl_add_u64 v[168:169], v[168:169], 0, s[34:35]
	v_cvt_pk_bf16_f32 v162, v36, v37
	v_cvt_pk_bf16_f32 v163, v38, v39
	v_cvt_pk_bf16_f32 v164, v28, v29
	v_cvt_pk_bf16_f32 v165, v30, v31
	ds_write_b128 v152, v[162:165] offset:1024
	ds_read_b128 v[162:165], v153 offset:1024
	v_lshl_add_u64 v[168:169], v[168:169], 0, v[188:189]
	s_waitcnt lgkmcnt(2)
	global_store_dwordx4 v[170:171], v[154:157], off
	s_nop 1
	v_cvt_pk_bf16_f32 v154, v40, v41
	v_cvt_pk_bf16_f32 v155, v42, v43
	v_cvt_pk_bf16_f32 v156, v32, v33
	v_cvt_pk_bf16_f32 v157, v34, v35
	ds_write_b128 v152, v[154:157]
	v_add_u32_e32 v158, 0xa0, v144
	ds_read_b128 v[154:157], v153
	v_ashrrev_i32_e32 v159, 31, v158
	v_lshlrev_b64 v[158:159], 7, v[158:159]
	v_lshl_add_u64 v[160:161], s[46:47], 0, v[158:159]
	v_lshl_add_u64 v[160:161], v[160:161], 0, s[34:35]
	v_lshl_add_u64 v[160:161], v[160:161], 0, v[188:189]
	s_waitcnt lgkmcnt(2)
	global_store_dwordx4 v[168:169], v[162:165], off
	s_nop 1
	v_lshl_add_u64 v[158:159], s[48:49], 0, v[158:159]
	v_lshl_add_u64 v[158:159], v[158:159], 0, s[34:35]
	v_cvt_pk_bf16_f32 v162, v20, v21
	v_cvt_pk_bf16_f32 v163, v22, v23
	v_cvt_pk_bf16_f32 v164, v12, v13
	v_cvt_pk_bf16_f32 v165, v14, v15
	ds_write_b128 v152, v[162:165] offset:1024
	ds_read_b128 v[162:165], v153 offset:1024
	v_lshl_add_u64 v[158:159], v[158:159], 0, v[188:189]
	v_add_u32_e32 v144, 0xb0, v144
	v_ashrrev_i32_e32 v145, 31, v144
	v_lshlrev_b64 v[144:145], 7, v[144:145]
	s_waitcnt lgkmcnt(2)
	global_store_dwordx4 v[160:161], v[154:157], off
	s_nop 1
	v_lshl_add_u64 v[168:169], s[46:47], 0, v[144:145]
	v_lshl_add_u64 v[168:169], v[168:169], 0, s[34:35]
	v_cvt_pk_bf16_f32 v154, v24, v25
	v_cvt_pk_bf16_f32 v155, v26, v27
	v_cvt_pk_bf16_f32 v156, v16, v17
	v_cvt_pk_bf16_f32 v157, v18, v19
	ds_write_b128 v152, v[154:157]
	ds_read_b128 v[154:157], v153
	v_lshl_add_u64 v[168:169], v[168:169], 0, v[188:189]
	v_lshl_add_u64 v[144:145], s[48:49], 0, v[144:145]
	v_lshl_add_u64 v[144:145], v[144:145], 0, s[34:35]
	v_lshl_add_u64 v[144:145], v[144:145], 0, v[188:189]
	s_waitcnt lgkmcnt(2)
	global_store_dwordx4 v[158:159], v[162:165], off
	s_nop 1
	v_cvt_pk_bf16_f32 v162, v8, v9
	v_cvt_pk_bf16_f32 v163, v10, v11
	v_cvt_pk_bf16_f32 v164, v4, v5
	v_cvt_pk_bf16_f32 v165, v6, v7
	ds_write_b128 v152, v[162:165] offset:1024
	ds_read_b128 v[162:165], v153 offset:1024
	s_waitcnt lgkmcnt(2)
	global_store_dwordx4 v[168:169], v[154:157], off
	s_nop 1
	s_waitcnt lgkmcnt(0)
	global_store_dwordx4 v[144:145], v[162:165], off
	s_cbranch_scc1 .LBB0_181
	v_readlane_b32 s94, v255, 33
	v_readlane_b32 s96, v255, 19
	s_cmp_gt_i32 s64, 12
	v_readlane_b32 s95, v255, 34
	v_readlane_b32 s97, v255, 20
	s_cbranch_scc0 .LBB0_182
	s_cmp_eq_u32 s64, 13
	s_cselect_b64 s[46:47], -1, 0
	s_cbranch_execz .LBB0_183
	s_branch .LBB0_184
